# SSD: per-chunk dt softplus + decay scan (was wave 0 only, 7 waves idle at the barrier) now done by all 8 waves for 8 chunks at a time (ssd_scan8), stacked on v80
# speedup vs baseline: 1.0103x; 1.0049x over previous
; __device__ __forceinline__ void ssd_phase(const Args& A, unsigned char* smem, const bool dry) {
;     ...
;             SSD_ISSUE(0);
.LBB0_423:
	s_or_b64 exec, exec, s[18:19]
	v_cndmask_b32_e64 v0, v101, v100, s[92:93]
	v_cndmask_b32_e64 v2, v104, v103, s[92:93]
	s_waitcnt vmcnt(4)
	v_cndmask_b32_e64 v8, v107, v106, s[92:93]
	v_cndmask_b32_e64 v10, v110, v109, s[92:93]
	s_waitcnt vmcnt(2)
	v_cndmask_b32_e64 v16, v113, v112, s[92:93]
	v_or_b32_e32 v0, s40, v0
	v_or_b32_e32 v2, s40, v2
	v_or_b32_e32 v8, s40, v8
	v_or_b32_e32 v10, s40, v10
	v_or_b32_e32 v16, s40, v16
	v_mad_i64_i32 v[0:1], s[18:19], v0, s33, v[58:59]
	v_mad_i64_i32 v[4:5], s[18:19], v2, s33, v[60:61]
	v_mad_i64_i32 v[8:9], s[18:19], v8, s33, v[62:63]
	v_mad_i64_i32 v[12:13], s[18:19], v10, s33, v[64:65]
	v_mad_i64_i32 v[16:17], s[18:19], v16, s33, v[66:67]
	global_load_dwordx4 v[0:3], v[0:1], off
	s_nop 0
	global_load_dwordx4 v[4:7], v[4:5], off
	s_nop 0
	global_load_dwordx4 v[8:11], v[8:9], off
	s_nop 0
	global_load_dwordx4 v[12:15], v[12:13], off
	s_mov_b32 s15, s94
	global_load_dwordx4 v[16:19], v[16:17], off
	v_mov_b64_e32 v[22:23], s[14:15]
	s_and_saveexec_b64 s[18:19], s[2:3]
	s_xor_b64 s[18:19], exec, s[18:19]
	v_mov_b64_e32 v[22:23], s[14:15]
	s_or_saveexec_b64 s[18:19], s[18:19]
	v_mov_b32_e32 v20, 0
	v_mov_b32_e32 v167, 0
	v_cndmask_b32_e64 v24, v98, v152, s[92:93]
	v_or_b32_e32 v24, s40, v24
	v_ashrrev_i32_e32 v25, 31, v24
	v_readlane_b32 s22, v251, 52
	v_lshlrev_b64 v[24:25], 7, v[24:25]
	v_readlane_b32 s23, v251, 53
	s_nop 1
	v_lshl_add_u64 v[24:25], s[22:23], 0, v[24:25]
	v_lshl_add_u64 v[24:25], s[14:15], 2, v[24:25]
	s_lshl_b32 s14, s37, 2
	s_mov_b32 s15, s94
	v_lshl_add_u64 v[24:25], v[24:25], 0, s[14:15]
	global_load_dword v167, v[24:25], off

; __device__ __forceinline__ void ssd_phase(const Args& A, unsigned char* smem, const bool dry) {
;     ...
;             for (int bt = 0; bt < 64; ++bt) {
;                 u16* Xb = Xb0 + (bt & 1) * (64 * 72);
; #pragma unroll
;                 for (int k = 0; k < 5; ++k) { const int it_ = tid + 512 * k; const int o = it_ % 40, i = it_ / 40;
;                     if (o < 8) *(u32x4*)(Xb + i * 72 + 8 * o) = pre[k];
;                     else if (o < 24) *(u32x4*)(Bb + i * 136 + 8 * (o - 8)) = pre[k];
;                     else *(u32x4*)(Cb + i * 136 + 8 * (o - 24)) = pre[k]; }
;                 if (tid < 64) {
;                     const float v = dpre + dtb; const float dt = v > 20.f ? v : log1pf(__expf(v));
;                     float c = dt * a_neg;
; #pragma unroll
;                     for (int d = 1; d < 64; d <<= 1) { const float tv = __shfl_up(c, d); if (lane >= d) c += tv; }
;                     const float tot = __shfl(c, 63);
;                     cumv[lane] = c; dtv[lane] = dt; wv[lane] = dt * __expf(tot - c); ecv[lane] = __expf(c); if (lane == 0) etot[0] = __expf(tot); }
;                 if (bt + 1 < 64) { SSD_ISSUE(bt + 1); }
;                 __syncthreads();
.LBB0_428:
	s_add_i32 s23, s23, 64
	s_sub_i32 s22, s22, 64
	s_add_i32 s26, s26, 1
	s_and_b32 s14, s26, 7
	s_movk_i32 s15, 0x500
	s_cmp_eq_u32 s14, 0
	s_cselect_b32 s14, 0xffffdd00, s15
	v_add_u32_e32 v83, s14, v83
	v_add_u32_e32 v87, s14, v87
	v_add_u32_e32 v135, s14, v135
	v_add_u32_e32 v136, s14, v136
	v_add_u32_e32 v92, s14, v92
	s_add_i32 s30, s30, s14
	s_cmpk_eq_i32 s23, 0x1000
	s_cbranch_scc1 .LBB0_416

; __device__ __forceinline__ void ssd_phase(const Args& A, unsigned char* smem, const bool dry) {
;     ...
;                 if (tid < 64) {
;                     const float v = dpre + dtb; const float dt = v > 20.f ? v : log1pf(__expf(v));
;                     float c = dt * a_neg;
; #pragma unroll
;                     for (int d = 1; d < 64; d <<= 1) { const float tv = __shfl_up(c, d); if (lane >= d) c += tv; }
;                     const float tot = __shfl(c, 63);
;                     cumv[lane] = c; dtv[lane] = dt; wv[lane] = dt * __expf(tot - c); ecv[lane] = __expf(c); if (lane == 0) etot[0] = __expf(tot); }
;                 if (bt + 1 < 64) { SSD_ISSUE(bt + 1); }
.LBB0_439:
	s_or_b64 exec, exec, s[14:15]
	s_mov_b64 s[74:75], exec
	s_and_b32 s14, s26, 7
	s_cmp_lg_u32 s14, 0
	s_cbranch_scc0 .LBB0_470
	s_branch .LBB0_474

; __device__ __forceinline__ void ssd_phase(const Args& A, unsigned char* smem, const bool dry) {
;     ...
;                 if (tid < 64) {
;                     const float v = dpre + dtb; const float dt = v > 20.f ? v : log1pf(__expf(v));
;                     float c = dt * a_neg;
; #pragma unroll
;                     for (int d = 1; d < 64; d <<= 1) { const float tv = __shfl_up(c, d); if (lane >= d) c += tv; }
;                     const float tot = __shfl(c, 63);
;                     cumv[lane] = c; dtv[lane] = dt; wv[lane] = dt * __expf(tot - c); ecv[lane] = __expf(c); if (lane == 0) etot[0] = __expf(tot); }
;                 if (bt + 1 < 64) { SSD_ISSUE(bt + 1); }
.LBB0_469:
	s_waitcnt lgkmcnt(0)
	v_add3_u32 v36, s7, v134, v131
	s_waitcnt vmcnt(1)
	ds_write_b128 v36, v[16:19] offset:52224
	s_or_b64 exec, exec, s[14:15]
	s_mov_b64 s[74:75], exec
	s_and_b32 s14, s26, 7
	s_cmp_lg_u32 s14, 0
	s_cbranch_scc1 .LBB0_474

; __device__ __forceinline__ void ssd_phase(const Args& A, unsigned char* smem, const bool dry) {
;     ...
;                 if (tid < 64) {
;                     const float v = dpre + dtb; const float dt = v > 20.f ? v : log1pf(__expf(v));
;                     float c = dt * a_neg;
; #pragma unroll
;                     for (int d = 1; d < 64; d <<= 1) { const float tv = __shfl_up(c, d); if (lane >= d) c += tv; }
;                     const float tot = __shfl(c, 63);
;                     cumv[lane] = c; dtv[lane] = dt; wv[lane] = dt * __expf(tot - c); ecv[lane] = __expf(c); if (lane == 0) etot[0] = __expf(tot); }
;                 if (bt + 1 < 64) { SSD_ISSUE(bt + 1); }
;                 __syncthreads();
.LBB0_472:
	s_or_b64 exec, exec, s[14:15]
	v_lshrrev_b32_e32 v79, 6, v152
	v_mul_u32_u24_e32 v79, 0x500, v79
	v_lshl_add_u32 v79, v164, 2, v79
	v_add_u32_e32 v79, 0x19c00, v79
	v_and_b32_e32 v38, 64, v164
	v_add_u32_e32 v39, -1, v164
	v_cmp_lt_i32_e32 vcc, v39, v38
	v_mul_f32_e64 v37, v36, -v168
	v_add_u32_e32 v40, -2, v164
	v_cndmask_b32_e32 v39, v39, v164, vcc
	v_lshlrev_b32_e32 v39, 2, v39
	ds_bpermute_b32 v39, v39, v37
	v_cmp_lt_i32_e32 vcc, v40, v38
	ds_write_b32 v79, v36 offset:256
	s_waitcnt lgkmcnt(1)
	v_fma_f32 v39, v36, -v168, v39
	v_cndmask_b32_e64 v37, v39, v37, s[4:5]
	v_cndmask_b32_e32 v39, v40, v164, vcc
	v_lshlrev_b32_e32 v39, 2, v39
	ds_bpermute_b32 v39, v39, v37
	v_add_u32_e32 v40, -4, v164
	v_cmp_lt_i32_e32 vcc, v40, v38
	s_waitcnt lgkmcnt(0)
	v_add_f32_e32 v39, v37, v39
	v_cndmask_b32_e64 v37, v39, v37, s[48:49]
	v_cndmask_b32_e32 v39, v40, v164, vcc
	v_lshlrev_b32_e32 v39, 2, v39
	ds_bpermute_b32 v39, v39, v37
	v_add_u32_e32 v40, -8, v164
	v_cmp_lt_i32_e32 vcc, v40, v38
	s_waitcnt lgkmcnt(0)
	v_add_f32_e32 v39, v37, v39
	v_cndmask_b32_e64 v37, v39, v37, s[50:51]
	v_cndmask_b32_e32 v39, v40, v164, vcc
	v_lshlrev_b32_e32 v39, 2, v39
	ds_bpermute_b32 v39, v39, v37
	v_add_u32_e32 v40, -16, v164
	v_cmp_lt_i32_e32 vcc, v40, v38
	s_waitcnt lgkmcnt(0)
	v_add_f32_e32 v39, v37, v39
	v_cndmask_b32_e64 v37, v39, v37, s[52:53]
	v_cndmask_b32_e32 v39, v40, v164, vcc
	v_lshlrev_b32_e32 v39, 2, v39
	ds_bpermute_b32 v39, v39, v37
	v_subrev_u32_e32 v40, 32, v164
	v_cmp_lt_i32_e32 vcc, v40, v38
	s_waitcnt lgkmcnt(0)
	v_add_f32_e32 v39, v37, v39
	v_cndmask_b32_e32 v38, v40, v164, vcc
	v_cndmask_b32_e64 v37, v39, v37, s[54:55]
	v_lshlrev_b32_e32 v38, 2, v38
	ds_bpermute_b32 v38, v38, v37
	s_waitcnt lgkmcnt(0)
	v_add_f32_e32 v38, v37, v38
	v_cndmask_b32_e64 v38, v38, v37, s[56:57]
	ds_bpermute_b32 v37, v165, v38
	v_mul_f32_e32 v40, 0x3fb8aa3b, v38
	v_exp_f32_e32 v40, v40
	ds_write_b32 v79, v38
	s_waitcnt lgkmcnt(1)
	v_sub_f32_e32 v39, v37, v38
	v_mul_f32_e32 v39, 0x3fb8aa3b, v39
	v_exp_f32_e32 v39, v39
	s_nop 0
	v_mul_f32_e32 v36, v36, v39
	ds_write_b32 v79, v36 offset:512
	ds_write_b32 v79, v40 offset:768
	s_and_b64 exec, exec, s[4:5]
	s_cbranch_execz .LBB0_474
	v_mul_f32_e32 v36, 0x3fb8aa3b, v37
	v_exp_f32_e32 v36, v36
	ds_write_b32 v79, v36 offset:1024
.LBB0_474:
	s_or_b64 exec, exec, s[74:75]
	s_cmpk_eq_i32 s23, 0xfc0
	s_cbranch_scc1 .LBB0_478
	s_waitcnt vmcnt(5)
	v_add_u32_e32 v0, s23, v149
	v_add_u32_e32 v1, s22, v150
	v_add_u32_e32 v2, s23, v147
	v_add_u32_e32 v3, s22, v148
	s_waitcnt vmcnt(3)
	v_add_u32_e32 v8, s23, v145
	v_add_u32_e32 v9, s22, v146
	v_add_u32_e32 v10, s23, v143
	v_add_u32_e32 v11, s22, v144
	s_waitcnt vmcnt(1)
	v_add_u32_e32 v16, s23, v141
	v_add_u32_e32 v17, s22, v142
	v_cndmask_b32_e64 v0, v1, v0, s[92:93]
	v_cndmask_b32_e64 v2, v3, v2, s[92:93]
	v_cndmask_b32_e64 v8, v9, v8, s[92:93]
	v_cndmask_b32_e64 v10, v11, v10, s[92:93]
	v_cndmask_b32_e64 v16, v17, v16, s[92:93]
	v_add_u32_e32 v0, s40, v0
	v_add_u32_e32 v2, s40, v2
	v_add_u32_e32 v8, s40, v8
	v_add_u32_e32 v10, s40, v10
	v_add_u32_e32 v16, s40, v16
	v_mad_i64_i32 v[0:1], s[14:15], v0, s33, v[58:59]
	v_mad_i64_i32 v[4:5], s[14:15], v2, s33, v[60:61]
	v_mad_i64_i32 v[8:9], s[14:15], v8, s33, v[62:63]
	v_mad_i64_i32 v[12:13], s[14:15], v10, s33, v[64:65]
	v_mad_i64_i32 v[16:17], s[14:15], v16, s33, v[66:67]
	global_load_dwordx4 v[0:3], v[0:1], off
	s_nop 0
	global_load_dwordx4 v[4:7], v[4:5], off
	s_nop 0
	global_load_dwordx4 v[8:11], v[8:9], off
	s_nop 0
	global_load_dwordx4 v[12:15], v[12:13], off
	s_nop 0
	global_load_dwordx4 v[16:19], v[16:17], off
	s_and_b32 s14, s26, 7
	s_cmp_lg_u32 s14, 0
	s_cbranch_scc1 .LBB0_477
	s_cmpk_ge_u32 s23, 0xe00
	s_cbranch_scc1 .LBB0_477
	s_waitcnt lgkmcnt(0)
	v_add_u32_e32 v36, s22, v98
	v_add_u32_e32 v37, s23, v152
	v_subrev_u32_e32 v36, 0x200, v36
	v_add_u32_e32 v37, 0x200, v37
	v_cndmask_b32_e64 v36, v36, v37, s[92:93]
	v_add_u32_e32 v36, s40, v36
	v_ashrrev_i32_e32 v37, 31, v36
	v_lshlrev_b64 v[36:37], 7, v[36:37]
	v_lshl_add_u64 v[36:37], v[68:69], 0, v[36:37]
	global_load_dword v167, v[36:37], off
.LBB0_477:
.LBB0_478:
	v_lshlrev_b32_e32 v46, 1, v44
	v_add3_u32 v53, s7, v84, v46
	s_waitcnt lgkmcnt(0)
	s_barrier
	ds_read_b128 v[36:39], v53 offset:52224
	ds_read_b32 v40, v83
	s_waitcnt lgkmcnt(1)
	v_lshlrev_b32_e32 v42, 16, v36
	v_and_b32_e32 v43, 0xffff0000, v36
	v_lshlrev_b32_e32 v36, 16, v37
	v_and_b32_e32 v37, 0xffff0000, v37
	s_waitcnt lgkmcnt(0)
	v_pk_mul_f32 v[70:71], v[40:41], v[36:37] op_sel_hi:[0,1]
	v_lshlrev_b32_e32 v36, 16, v38
	v_and_b32_e32 v37, 0xffff0000, v38
	v_pk_mul_f32 v[72:73], v[40:41], v[36:37] op_sel_hi:[0,1]
	v_lshlrev_b32_e32 v36, 16, v39
	v_and_b32_e32 v37, 0xffff0000, v39
	v_pk_mul_f32 v[42:43], v[40:41], v[42:43] op_sel_hi:[0,1]
	v_pk_mul_f32 v[40:41], v[40:41], v[36:37] op_sel_hi:[0,1]
	v_cvt_pk_bf16_f32 v36, v42, v43
	v_cvt_pk_bf16_f32 v37, v70, v71
	v_cvt_pk_bf16_f32 v38, v72, v73
	v_cvt_pk_bf16_f32 v39, v40, v41
	ds_write_b128 v85, v[36:39]
	ds_read_b128 v[40:43], v154 offset:64
	ds_read_b128 v[70:73], v154 offset:128
	ds_read_b128 v[36:39], v155 offset:17472
	ds_read_b128 v[74:77], v155 offset:17536
	ds_read_b128 v[170:173], v155 offset:17600
	ds_read_b128 v[174:177], v155 offset:21760
	ds_read_b128 v[178:181], v155 offset:21824
	ds_read_b128 v[182:185], v155 offset:21888
	ds_read_b128 v[186:189], v155 offset:21952
	ds_read_b128 v[190:193], v154 offset:192
	ds_read_b128 v[194:197], v155 offset:34816
	ds_read_b128 v[198:201], v155 offset:34880
	ds_read_b128 v[202:205], v155 offset:34944
	ds_read_b128 v[206:209], v155 offset:35008
	ds_read_b128 v[210:213], v155 offset:39168
	ds_read_b128 v[214:217], v155 offset:39232
	ds_read_b128 v[218:221], v155 offset:39296
	ds_read_b128 v[222:225], v155 offset:17408
	ds_read_b128 v[226:229], v155 offset:39360
	ds_read_b32 v169, v87
	ds_read_b128 v[230:233], v135
	ds_read_b128 v[234:237], v136
	ds_read_b128 v[238:241], v135 offset:64
	ds_read_b128 v[242:245], v154
	ds_read_b128 v[246:249], v136 offset:64
	s_waitcnt lgkmcnt(1)
; __device__ __forceinline__ void ssd_phase(const Args& A, unsigned char* smem, const bool dry) {
;     ...
;                     const int i = 16 * it + r16; const float ci = cumv[i];
;                     f32x4 cj[2], dj[2];
; #pragma unroll
;                     for (int jj = 0; jj < 2; ++jj) { cj[jj] = *(const f32x4*)(cumv + 16 * (2 * hh + jj) + 4 * q4); dj[jj] = *(const f32x4*)(dtv + 16 * (2 * hh + jj) + 4 * q4); }
;                     __builtin_amdgcn_sched_barrier(0);
;                     f32x4 gacc[2];
; #pragma unroll
;                     for (int jj = 0; jj < 2; ++jj) { gacc[jj] = (f32x4){0.f, 0.f, 0.f, 0.f};
; #pragma unroll
;                         for (int ks = 0; ks < 4; ++ks) gacc[jj] = __builtin_amdgcn_mfma_f32_16x16x32_bf16(bfr[jj][ks], cf[ks], gacc[jj], 0, 0, 0); }
; #pragma unroll
;                     for (int pp = 0; pp < 2; ++pp) { yst[pp] = (f32x4){0.f, 0.f, 0.f, 0.f};
; #pragma unroll
;                         for (int ks = 0; ks < 4; ++ks) yst[pp] = __builtin_amdgcn_mfma_f32_16x16x32_bf16(cf[ks], sf[pp][ks], yst[pp], 0, 0, 0); }
; #pragma unroll
;                     for (int jj = 0; jj < 2; ++jj) { const int jt = 2 * hh + jj; float m[4];
; #pragma unroll
;                         for (int r = 0; r < 4; ++r) { const int j = 16 * jt + 4 * q4 + r; m[r] = (j <= i) ? gacc[jj][r] * __expf(ci - cj[jj][r]) * dj[jj][r] : 0.f; }
;                         u32x2 outw; outw.x = pk2(m[0], m[1]); outw.y = pk2(m[2], m[3]);
;                         *(u32x2*)(Mb + (16 * it + r16) * 72 + 16 * jt + 4 * q4) = outw; }
;                 }
;                 __syncthreads();
;                 {
;                     bf16x8 mf[2], xf[2][2], af[2], xwf[4][2];
; #pragma unroll
;                     for (int ks = 0; ks < 2; ++ks) mf[ks] = *(const bf16x8*)(Mb + (16 * it + r16) * 72 + 32 * ks + 8 * q4);
; #pragma unroll
;                     for (int pp = 0; pp < 2; ++pp)
; #pragma unroll
;                         for (int ks = 0; ks < 2; ++ks) xf[pp][ks] = tr_frag(Xb, 72, 32 * ks, 16 * (2 * hh + pp), lane);
; #pragma unroll
;                     for (int ks = 0; ks < 2; ++ks) af[ks] = tr_frag(Bb, 136, 32 * ks, 16 * wave, lane);
; #pragma unroll
;                     for (int pt = 0; pt < 4; ++pt)
; #pragma unroll
;                         for (int ks = 0; ks < 2; ++ks) xwf[pt][ks] = tr_frag(XWb, 72, 32 * ks, 16 * pt, lane);
	v_mfma_f32_16x16x32_bf16 v[222:225], v[222:225], v[242:245], 0
	v_sub_f32_e32 v78, v169, v230
	v_mul_f32_e32 v78, 0x3fb8aa3b, v78
	v_exp_f32_e32 v79, v78
	v_mfma_f32_16x16x32_bf16 v[36:39], v[36:39], v[40:43], v[222:225]
	v_sub_f32_e32 v78, v169, v231
	v_mul_f32_e32 v78, 0x3fb8aa3b, v78
	v_mfma_f32_16x16x32_bf16 v[36:39], v[74:77], v[70:73], v[36:39]
	s_nop 0
	v_exp_f32_e32 v222, v78
	v_sub_f32_e32 v78, v169, v232
	v_mul_f32_e32 v74, 0x3fb8aa3b, v78
	v_mfma_f32_16x16x32_bf16 v[36:39], v[170:173], v[190:193], v[36:39]
	v_exp_f32_e32 v78, v74
	v_sub_f32_e32 v223, v169, v233
	v_mfma_f32_16x16x32_bf16 v[74:77], v[174:177], v[242:245], 0
	v_mfma_f32_16x16x32_bf16 v[74:77], v[178:181], v[40:43], v[74:77]
	s_nop 3
	v_mul_f32_e32 v36, v79, v36
	v_mul_f32_e32 v36, v234, v36
	v_cndmask_b32_e64 v170, v36, 0, s[58:59]
	v_mul_f32_e32 v36, 0x3fb8aa3b, v223
	v_exp_f32_e32 v79, v36
	v_mul_f32_e32 v37, v222, v37
	v_mul_f32_e32 v36, v235, v37
	v_cndmask_b32_e64 v171, 0, v36, s[60:61]
	v_pk_mul_f32 v[36:37], v[78:79], v[38:39]
	v_cvt_pk_bf16_f32 v170, v170, v171
	v_pk_mul_f32 v[78:79], v[236:237], v[36:37]
	v_mfma_f32_16x16x32_bf16 v[36:39], v[182:185], v[70:73], v[74:77]
	v_cvt_pk_bf16_f32 v78, v78, v79
	v_cndmask_b32_e64 v79, v78, 0, s[64:65]
	v_mfma_f32_16x16x32_bf16 v[74:77], v[186:189], v[190:193], v[36:39]
	s_nop 4
	v_lshrrev_b32_e32 v36, 16, v78
	v_sub_f32_e32 v78, v169, v238
	v_mul_f32_e32 v78, 0x3fb8aa3b, v78
	v_exp_f32_e32 v78, v78
	v_cndmask_b32_e64 v36, v36, 0, s[62:63]
	v_perm_b32 v171, v36, v79, s31
	v_add_u32_e32 v79, v89, v90
	v_mul_f32_e32 v74, v78, v74
	v_sub_f32_e32 v78, v169, v239
	v_mul_f32_e32 v78, 0x3fb8aa3b, v78
	v_exp_f32_e32 v78, v78
	v_mfma_f32_16x16x32_bf16 v[36:39], v[242:245], v[194:197], 0
	ds_write_b64 v79, v[170:171]
	s_waitcnt lgkmcnt(1)
	v_mul_f32_e32 v74, v246, v74
	v_cndmask_b32_e64 v79, v74, 0, s[66:67]
	v_mfma_f32_16x16x32_bf16 v[170:173], v[242:245], v[210:213], 0
	v_mul_f32_e32 v78, v78, v75
	v_sub_f32_e32 v74, v169, v240
	v_sub_f32_e32 v75, v169, v241
	v_mfma_f32_16x16x32_bf16 v[36:39], v[40:43], v[198:201], v[36:39]
	v_mul_f32_e32 v74, 0x3fb8aa3b, v74
	v_mul_f32_e32 v75, 0x3fb8aa3b, v75
	v_exp_f32_e32 v74, v74
	v_mfma_f32_16x16x32_bf16 v[40:43], v[40:43], v[214:217], v[170:173]
	v_exp_f32_e32 v75, v75
	v_mfma_f32_16x16x32_bf16 v[36:39], v[70:73], v[202:205], v[36:39]
	v_mfma_f32_16x16x32_bf16 v[40:43], v[70:73], v[218:221], v[40:43]
	v_mul_f32_e32 v70, v247, v78
	v_cndmask_b32_e64 v72, 0, v70, s[68:69]
	v_pk_mul_f32 v[70:71], v[74:75], v[76:77]
	v_cvt_pk_bf16_f32 v72, v79, v72
	v_pk_mul_f32 v[70:71], v[248:249], v[70:71]
	v_add_u32_e32 v78, v88, v86
	v_cvt_pk_bf16_f32 v70, v70, v71
	v_cndmask_b32_e64 v71, v70, 0, s[72:73]
	v_lshrrev_b32_e32 v70, 16, v70
	v_cndmask_b32_e64 v70, v70, 0, s[70:71]
	v_perm_b32 v73, v70, v71, s31
	v_add_u32_e32 v70, s7, v90
	v_mfma_f32_16x16x32_bf16 v[36:39], v[190:193], v[206:209], v[36:39]
	ds_write_b64 v156, v[72:73]
	s_waitcnt lgkmcnt(0)
	s_barrier
	v_add3_u32 v79, v70, v91, v137
	ds_read_b128 v[70:73], v78 offset:64
	ds_read_b64_tr_b16 v[74:75], v79 offset:52224
	ds_read_b64_tr_b16 v[76:77], v79 offset:52800
	ds_read_b64_tr_b16 v[170:171], v79 offset:56832
	ds_read_b64_tr_b16 v[176:177], v79 offset:52832
	ds_read_b64_tr_b16 v[174:175], v79 offset:52256
	ds_read_b64_tr_b16 v[172:173], v79 offset:57408
	ds_read_b64_tr_b16 v[180:181], v79 offset:57440
	ds_read_b64_tr_b16 v[182:183], v157 offset:17408
	ds_read_b64_tr_b16 v[178:179], v79 offset:56864
	ds_read_b64_tr_b16 v[184:185], v157 offset:18496
	ds_read_b64_tr_b16 v[186:187], v157 offset:26112
	ds_read_b64_tr_b16 v[188:189], v157 offset:27200
	ds_read_b64_tr_b16 v[194:195], v158
	ds_read_b64_tr_b16 v[196:197], v158 offset:576
	ds_read_b64_tr_b16 v[198:199], v158 offset:32
	ds_read_b64_tr_b16 v[202:203], v158 offset:64
	ds_read_b64_tr_b16 v[206:207], v158 offset:96
	ds_read_b64_tr_b16 v[210:211], v158 offset:4608
	ds_read_b64_tr_b16 v[200:201], v158 offset:608
	ds_read_b64_tr_b16 v[204:205], v158 offset:640
	ds_read_b64_tr_b16 v[208:209], v158 offset:672
	ds_read_b64_tr_b16 v[212:213], v158 offset:5184
	ds_read_b64_tr_b16 v[214:215], v158 offset:4640
	ds_read_b64_tr_b16 v[218:219], v158 offset:4672
	ds_read_b64_tr_b16 v[222:223], v158 offset:4704
	ds_read_b128 v[230:233], v78
	ds_read_b128 v[234:237], v92
	v_mov_b32_e32 v78, s30
	ds_read_b64_tr_b16 v[216:217], v158 offset:5216
	ds_read_b64_tr_b16 v[220:221], v158 offset:5248
	ds_read_b64_tr_b16 v[224:225], v158 offset:5280
	ds_read_b32 v78, v78
	s_cmp_eq_u64 s[10:11], 0
	s_cbranch_scc1 .Lssd_pf_skip
	v_add_u32_e32 v238, s22, v99
	v_add_u32_e32 v239, s23, v82
	v_cndmask_b32_e64 v238, v238, v239, s[92:93]
	v_add_u32_e32 v240, s40, v238
	v_ashrrev_i32_e32 v241, 31, v240
	v_lshlrev_b64 v[238:239], 11, v[240:241]
	v_lshl_add_u64 v[238:239], v[56:57], 0, v[238:239]
	v_mov_b64_e32 v[246:247], s[96:97]
	v_mad_i64_i32 v[240:241], s[14:15], v240, s33, v[246:247]
	v_lshlrev_b32_e32 v246, 1, v44
	v_add_u32_e32 v246, s6, v246
	v_mov_b32_e32 v247, 0
	v_lshl_add_u64 v[240:241], v[240:241], 0, v[246:247]
	v_add_co_u32_e32 v240, vcc, 0x1000, v240
	s_nop 1
	v_addc_co_u32_e32 v241, vcc, 0, v241, vcc
	global_load_dwordx4 v[242:245], v[238:239], off
	s_nop 0
	global_load_dwordx4 v[246:249], v[240:241], off offset:2048
